# grid barrier release: waiting workgroups poll the cross-XCD generation word directly (one relay hop less per barrier, 14 barriers); on top of v89
# speedup vs baseline: 1.0038x; 1.0038x over previous
; __device__ __forceinline__ unsigned xb_ld(unsigned* p)              { return __hip_atomic_load(p, __ATOMIC_RELAXED, __HIP_MEMORY_SCOPE_AGENT); }
; __device__ __forceinline__ unsigned xb_add(unsigned* p, unsigned v) { return __hip_atomic_fetch_add(p, v, __ATOMIC_RELAXED, __HIP_MEMORY_SCOPE_AGENT); }
; #define XB_SPIN(cond, bar) do { unsigned _sp = 0; while (cond) { __builtin_amdgcn_s_sleep(1); \
;     if ((++_sp & 255u) == 0u) { if (xb_ld(&(bar)[XB_TMO])) break; if (_sp > XB_SPIN_CAP) { atomicAdd(&(bar)[XB_TMO], 1u); break; } } } } while (0)
; __device__ __forceinline__ void xcd_barrier(const XcdBarrier& b) {
;     ...
;         const unsigned old = xb_add(&bar[XB_XSUB(b.x)], 1u);
;         const unsigned gen = old / nloc;
;         if (old + 1u == (gen + 1u) * nloc) {
;             __builtin_amdgcn_fence(__ATOMIC_RELEASE, "agent");
;             asm volatile("s_waitcnt vmcnt(0)" ::: "memory");
;             const unsigned og = xb_add(&bar[XB_TOP], 1u);
;             const unsigned tg = og / nx;
;             if (og + 1u == (tg + 1u) * nx) xb_add(&bar[XB_TOPGEN], 1u);
;             else XB_SPIN(xb_ld(&bar[XB_TOPGEN]) == tg, bar);
;             __builtin_amdgcn_fence(__ATOMIC_ACQUIRE, "agent");
;             xb_add(&bar[XB_XGEN(b.x)], 1u);
;             asm volatile("s_waitcnt vmcnt(0)" ::: "memory");
;         } else {
;             XB_SPIN(xb_ld(&bar[XB_XGEN(b.x)]) == gen, bar);
.LBB0_139:
	s_or_b64 exec, exec, s[24:25]
	v_cvt_f32_u32_e32 v5, v3
	s_waitcnt vmcnt(0)
	v_readfirstlane_b32 s3, v4
	v_sub_u32_e32 v4, 0, v3
	v_rcp_iflag_f32_e32 v5, v5
	v_add_u32_e32 v6, s3, v2
	v_mul_f32_e32 v5, 0x4f7ffffe, v5
	v_cvt_u32_f32_e32 v5, v5
	v_mul_lo_u32 v2, v4, v5
	v_mul_hi_u32 v2, v5, v2
	v_add_u32_e32 v2, v5, v2
	v_mul_hi_u32 v2, v6, v2
	v_mul_lo_u32 v4, v2, v3
	v_sub_u32_e32 v4, v6, v4
	v_add_u32_e32 v5, 1, v2
	v_cmp_ge_u32_e32 vcc, v4, v3
	s_nop 1
	v_cndmask_b32_e32 v2, v2, v5, vcc
	v_sub_u32_e32 v5, v4, v3
	v_cndmask_b32_e32 v4, v4, v5, vcc
	v_add_u32_e32 v5, 1, v2
	v_cmp_ge_u32_e32 vcc, v4, v3
	v_add_u32_e32 v4, 1, v6
	s_nop 0
	v_cndmask_b32_e32 v2, v2, v5, vcc
	v_mul_lo_u32 v5, v3, v2
	v_add_u32_e32 v3, v5, v3
	v_cmp_ne_u32_e32 vcc, v4, v3
	s_and_saveexec_b64 s[18:19], vcc
	s_xor_b64 s[22:23], exec, s[18:19]
	s_cbranch_execz .LBB0_153
	s_waitcnt lgkmcnt(0)
	v_mov_b32_e32 v1, 0x3500
	global_load_dword v1, v1, s[30:31] sc1
	s_add_u32 s26, s30, 0x3500
	s_addc_u32 s27, s31, 0
	s_waitcnt vmcnt(0)
	v_cmp_eq_u32_e32 vcc, v1, v2
	s_and_saveexec_b64 s[24:25], vcc
	s_cbranch_execz .LBB0_152
	s_mov_b32 s3, 1
	s_mov_b64 s[46:47], 0
	v_mov_b32_e32 v1, 0
	s_branch .LBB0_143

; __device__ __forceinline__ unsigned xb_ld(unsigned* p)              { return __hip_atomic_load(p, __ATOMIC_RELAXED, __HIP_MEMORY_SCOPE_AGENT); }
; __device__ __forceinline__ unsigned xb_add(unsigned* p, unsigned v) { return __hip_atomic_fetch_add(p, v, __ATOMIC_RELAXED, __HIP_MEMORY_SCOPE_AGENT); }
; #define XB_SPIN(cond, bar) do { unsigned _sp = 0; while (cond) { __builtin_amdgcn_s_sleep(1); \
;     if ((++_sp & 255u) == 0u) { if (xb_ld(&(bar)[XB_TMO])) break; if (_sp > XB_SPIN_CAP) { atomicAdd(&(bar)[XB_TMO], 1u); break; } } } } while (0)
; __device__ __forceinline__ void xcd_barrier(const XcdBarrier& b) {
;     ...
;         const unsigned old = xb_add(&bar[XB_XSUB(b.x)], 1u);
;         const unsigned gen = old / nloc;
;         if (old + 1u == (gen + 1u) * nloc) {
;             __builtin_amdgcn_fence(__ATOMIC_RELEASE, "agent");
;             asm volatile("s_waitcnt vmcnt(0)" ::: "memory");
;             const unsigned og = xb_add(&bar[XB_TOP], 1u);
;             const unsigned tg = og / nx;
;             if (og + 1u == (tg + 1u) * nx) xb_add(&bar[XB_TOPGEN], 1u);
;             else XB_SPIN(xb_ld(&bar[XB_TOPGEN]) == tg, bar);
;             __builtin_amdgcn_fence(__ATOMIC_ACQUIRE, "agent");
;             xb_add(&bar[XB_XGEN(b.x)], 1u);
;             asm volatile("s_waitcnt vmcnt(0)" ::: "memory");
;         } else {
;             XB_SPIN(xb_ld(&bar[XB_XGEN(b.x)]) == gen, bar);
.LBB0_206:
	s_or_b64 exec, exec, s[12:13]
	v_cvt_f32_u32_e32 v4, v2
	s_waitcnt vmcnt(0)
	v_readfirstlane_b32 s10, v3
	v_sub_u32_e32 v3, 0, v2
	v_rcp_iflag_f32_e32 v4, v4
	v_add_u32_e32 v5, s10, v1
	v_mul_f32_e32 v4, 0x4f7ffffe, v4
	v_cvt_u32_f32_e32 v4, v4
	v_mul_lo_u32 v1, v3, v4
	v_mul_hi_u32 v1, v4, v1
	v_add_u32_e32 v1, v4, v1
	v_mul_hi_u32 v1, v5, v1
	v_mul_lo_u32 v3, v1, v2
	v_sub_u32_e32 v3, v5, v3
	v_add_u32_e32 v4, 1, v1
	v_cmp_ge_u32_e32 vcc, v3, v2
	s_nop 1
	v_cndmask_b32_e32 v1, v1, v4, vcc
	v_sub_u32_e32 v4, v3, v2
	v_cndmask_b32_e32 v3, v3, v4, vcc
	v_add_u32_e32 v4, 1, v1
	v_cmp_ge_u32_e32 vcc, v3, v2
	v_add_u32_e32 v3, 1, v5
	s_nop 0
	v_cndmask_b32_e32 v1, v1, v4, vcc
	v_mul_lo_u32 v4, v2, v1
	v_add_u32_e32 v2, v4, v2
	v_cmp_ne_u32_e32 vcc, v3, v2
	s_and_saveexec_b64 s[10:11], vcc
	s_xor_b64 s[10:11], exec, s[10:11]
	s_cbranch_execz .LBB0_220
	s_waitcnt lgkmcnt(0)
	v_mov_b32_e32 v0, 0x3500
	global_load_dword v0, v0, s[30:31] sc1
	s_add_u32 s14, s30, 0x3500
	s_addc_u32 s15, s31, 0
	s_waitcnt vmcnt(0)
	v_cmp_eq_u32_e32 vcc, v0, v1
	s_and_saveexec_b64 s[12:13], vcc
	s_cbranch_execz .LBB0_219
	s_mov_b32 s18, 1
	s_mov_b64 s[26:27], 0
	v_mov_b32_e32 v0, 0
	s_branch .LBB0_210

; __device__ __forceinline__ unsigned xb_ld(unsigned* p)              { return __hip_atomic_load(p, __ATOMIC_RELAXED, __HIP_MEMORY_SCOPE_AGENT); }
; __device__ __forceinline__ unsigned xb_add(unsigned* p, unsigned v) { return __hip_atomic_fetch_add(p, v, __ATOMIC_RELAXED, __HIP_MEMORY_SCOPE_AGENT); }
; #define XB_SPIN(cond, bar) do { unsigned _sp = 0; while (cond) { __builtin_amdgcn_s_sleep(1); \
;     if ((++_sp & 255u) == 0u) { if (xb_ld(&(bar)[XB_TMO])) break; if (_sp > XB_SPIN_CAP) { atomicAdd(&(bar)[XB_TMO], 1u); break; } } } } while (0)
; __device__ __forceinline__ void xcd_barrier(const XcdBarrier& b) {
;     ...
;         const unsigned old = xb_add(&bar[XB_XSUB(b.x)], 1u);
;         const unsigned gen = old / nloc;
;         if (old + 1u == (gen + 1u) * nloc) {
;             __builtin_amdgcn_fence(__ATOMIC_RELEASE, "agent");
;             asm volatile("s_waitcnt vmcnt(0)" ::: "memory");
;             const unsigned og = xb_add(&bar[XB_TOP], 1u);
;             const unsigned tg = og / nx;
;             if (og + 1u == (tg + 1u) * nx) xb_add(&bar[XB_TOPGEN], 1u);
;             else XB_SPIN(xb_ld(&bar[XB_TOPGEN]) == tg, bar);
;             __builtin_amdgcn_fence(__ATOMIC_ACQUIRE, "agent");
;             xb_add(&bar[XB_XGEN(b.x)], 1u);
;             asm volatile("s_waitcnt vmcnt(0)" ::: "memory");
;         } else {
;             XB_SPIN(xb_ld(&bar[XB_XGEN(b.x)]) == gen, bar);
.LBB0_307:
	s_or_b64 exec, exec, s[12:13]
	v_cvt_f32_u32_e32 v4, v2
	s_waitcnt vmcnt(0)
	v_readfirstlane_b32 s10, v3
	v_sub_u32_e32 v3, 0, v2
	v_rcp_iflag_f32_e32 v4, v4
	v_add_u32_e32 v5, s10, v1
	v_mul_f32_e32 v4, 0x4f7ffffe, v4
	v_cvt_u32_f32_e32 v4, v4
	v_mul_lo_u32 v1, v3, v4
	v_mul_hi_u32 v1, v4, v1
	v_add_u32_e32 v1, v4, v1
	v_mul_hi_u32 v1, v5, v1
	v_mul_lo_u32 v3, v1, v2
	v_sub_u32_e32 v3, v5, v3
	v_add_u32_e32 v4, 1, v1
	v_cmp_ge_u32_e32 vcc, v3, v2
	s_nop 1
	v_cndmask_b32_e32 v1, v1, v4, vcc
	v_sub_u32_e32 v4, v3, v2
	v_cndmask_b32_e32 v3, v3, v4, vcc
	v_add_u32_e32 v4, 1, v1
	v_cmp_ge_u32_e32 vcc, v3, v2
	v_add_u32_e32 v3, 1, v5
	s_nop 0
	v_cndmask_b32_e32 v1, v1, v4, vcc
	v_mul_lo_u32 v4, v2, v1
	v_add_u32_e32 v2, v4, v2
	v_cmp_ne_u32_e32 vcc, v3, v2
	s_and_saveexec_b64 s[10:11], vcc
	s_xor_b64 s[10:11], exec, s[10:11]
	s_cbranch_execz .LBB0_321
	s_waitcnt lgkmcnt(0)
	v_mov_b32_e32 v0, 0x3500
	global_load_dword v0, v0, s[30:31] sc1
	s_add_u32 s14, s30, 0x3500
	s_addc_u32 s15, s31, 0
	s_waitcnt vmcnt(0)
	v_cmp_eq_u32_e32 vcc, v0, v1
	s_and_saveexec_b64 s[12:13], vcc
	s_cbranch_execz .LBB0_320
	s_mov_b32 s18, 1
	s_mov_b64 s[60:61], 0
	v_mov_b32_e32 v0, 0
	s_branch .LBB0_311

; __device__ __forceinline__ unsigned xb_ld(unsigned* p)              { return __hip_atomic_load(p, __ATOMIC_RELAXED, __HIP_MEMORY_SCOPE_AGENT); }
; __device__ __forceinline__ unsigned xb_add(unsigned* p, unsigned v) { return __hip_atomic_fetch_add(p, v, __ATOMIC_RELAXED, __HIP_MEMORY_SCOPE_AGENT); }
; #define XB_SPIN(cond, bar) do { unsigned _sp = 0; while (cond) { __builtin_amdgcn_s_sleep(1); \
;     if ((++_sp & 255u) == 0u) { if (xb_ld(&(bar)[XB_TMO])) break; if (_sp > XB_SPIN_CAP) { atomicAdd(&(bar)[XB_TMO], 1u); break; } } } } while (0)
; __device__ __forceinline__ void xcd_barrier(const XcdBarrier& b) {
;     ...
;         const unsigned old = xb_add(&bar[XB_XSUB(b.x)], 1u);
;         const unsigned gen = old / nloc;
;         if (old + 1u == (gen + 1u) * nloc) {
;             __builtin_amdgcn_fence(__ATOMIC_RELEASE, "agent");
;             asm volatile("s_waitcnt vmcnt(0)" ::: "memory");
;             const unsigned og = xb_add(&bar[XB_TOP], 1u);
;             const unsigned tg = og / nx;
;             if (og + 1u == (tg + 1u) * nx) xb_add(&bar[XB_TOPGEN], 1u);
;             else XB_SPIN(xb_ld(&bar[XB_TOPGEN]) == tg, bar);
;             __builtin_amdgcn_fence(__ATOMIC_ACQUIRE, "agent");
;             xb_add(&bar[XB_XGEN(b.x)], 1u);
;             asm volatile("s_waitcnt vmcnt(0)" ::: "memory");
;         } else {
;             XB_SPIN(xb_ld(&bar[XB_XGEN(b.x)]) == gen, bar);
.LBB0_389:
	s_or_b64 exec, exec, s[8:9]
	v_cvt_f32_u32_e32 v4, v2
	s_waitcnt vmcnt(0)
	v_readfirstlane_b32 s6, v3
	v_sub_u32_e32 v3, 0, v2
	v_rcp_iflag_f32_e32 v4, v4
	v_add_u32_e32 v5, s6, v1
	v_mul_f32_e32 v4, 0x4f7ffffe, v4
	v_cvt_u32_f32_e32 v4, v4
	v_mul_lo_u32 v1, v3, v4
	v_mul_hi_u32 v1, v4, v1
	v_add_u32_e32 v1, v4, v1
	v_mul_hi_u32 v1, v5, v1
	v_mul_lo_u32 v3, v1, v2
	v_sub_u32_e32 v3, v5, v3
	v_add_u32_e32 v4, 1, v1
	v_cmp_ge_u32_e32 vcc, v3, v2
	s_nop 1
	v_cndmask_b32_e32 v1, v1, v4, vcc
	v_sub_u32_e32 v4, v3, v2
	v_cndmask_b32_e32 v3, v3, v4, vcc
	v_add_u32_e32 v4, 1, v1
	v_cmp_ge_u32_e32 vcc, v3, v2
	v_add_u32_e32 v3, 1, v5
	s_nop 0
	v_cndmask_b32_e32 v1, v1, v4, vcc
	v_mul_lo_u32 v4, v2, v1
	v_add_u32_e32 v2, v4, v2
	v_cmp_ne_u32_e32 vcc, v3, v2
	s_and_saveexec_b64 s[6:7], vcc
	s_xor_b64 s[6:7], exec, s[6:7]
	s_cbranch_execz .LBB0_403
	s_waitcnt lgkmcnt(0)
	v_mov_b32_e32 v0, 0x3500
	global_load_dword v0, v0, s[30:31] sc1
	s_add_u32 s10, s30, 0x3500
	s_addc_u32 s11, s31, 0
	s_waitcnt vmcnt(0)
	v_cmp_eq_u32_e32 vcc, v0, v1
	s_and_saveexec_b64 s[8:9], vcc
	s_cbranch_execz .LBB0_402
	s_mov_b32 s16, 1
	s_mov_b64 s[12:13], 0
	v_mov_b32_e32 v0, 0
	s_branch .LBB0_393

; __device__ __forceinline__ unsigned xb_ld(unsigned* p)              { return __hip_atomic_load(p, __ATOMIC_RELAXED, __HIP_MEMORY_SCOPE_AGENT); }
; __device__ __forceinline__ unsigned xb_add(unsigned* p, unsigned v) { return __hip_atomic_fetch_add(p, v, __ATOMIC_RELAXED, __HIP_MEMORY_SCOPE_AGENT); }
; #define XB_SPIN(cond, bar) do { unsigned _sp = 0; while (cond) { __builtin_amdgcn_s_sleep(1); \
;     if ((++_sp & 255u) == 0u) { if (xb_ld(&(bar)[XB_TMO])) break; if (_sp > XB_SPIN_CAP) { atomicAdd(&(bar)[XB_TMO], 1u); break; } } } } while (0)
; __device__ __forceinline__ void xcd_barrier(const XcdBarrier& b) {
;     ...
;         const unsigned old = xb_add(&bar[XB_XSUB(b.x)], 1u);
;         const unsigned gen = old / nloc;
;         if (old + 1u == (gen + 1u) * nloc) {
;             __builtin_amdgcn_fence(__ATOMIC_RELEASE, "agent");
;             asm volatile("s_waitcnt vmcnt(0)" ::: "memory");
;             const unsigned og = xb_add(&bar[XB_TOP], 1u);
;             const unsigned tg = og / nx;
;             if (og + 1u == (tg + 1u) * nx) xb_add(&bar[XB_TOPGEN], 1u);
;             else XB_SPIN(xb_ld(&bar[XB_TOPGEN]) == tg, bar);
;             __builtin_amdgcn_fence(__ATOMIC_ACQUIRE, "agent");
;             xb_add(&bar[XB_XGEN(b.x)], 1u);
;             asm volatile("s_waitcnt vmcnt(0)" ::: "memory");
;         } else {
;             XB_SPIN(xb_ld(&bar[XB_XGEN(b.x)]) == gen, bar);
.LBB0_502:
	s_or_b64 exec, exec, s[8:9]
	v_cvt_f32_u32_e32 v4, v2
	s_waitcnt vmcnt(0)
	v_readfirstlane_b32 s6, v3
	v_sub_u32_e32 v3, 0, v2
	v_rcp_iflag_f32_e32 v4, v4
	v_add_u32_e32 v5, s6, v1
	v_mul_f32_e32 v4, 0x4f7ffffe, v4
	v_cvt_u32_f32_e32 v4, v4
	v_mul_lo_u32 v1, v3, v4
	v_mul_hi_u32 v1, v4, v1
	v_add_u32_e32 v1, v4, v1
	v_mul_hi_u32 v1, v5, v1
	v_mul_lo_u32 v3, v1, v2
	v_sub_u32_e32 v3, v5, v3
	v_add_u32_e32 v4, 1, v1
	v_cmp_ge_u32_e32 vcc, v3, v2
	s_nop 1
	v_cndmask_b32_e32 v1, v1, v4, vcc
	v_sub_u32_e32 v4, v3, v2
	v_cndmask_b32_e32 v3, v3, v4, vcc
	v_add_u32_e32 v4, 1, v1
	v_cmp_ge_u32_e32 vcc, v3, v2
	v_add_u32_e32 v3, 1, v5
	s_nop 0
	v_cndmask_b32_e32 v1, v1, v4, vcc
	v_mul_lo_u32 v4, v2, v1
	v_add_u32_e32 v2, v4, v2
	v_cmp_ne_u32_e32 vcc, v3, v2
	s_and_saveexec_b64 s[6:7], vcc
	s_xor_b64 s[6:7], exec, s[6:7]
	s_cbranch_execz .LBB0_516
	s_waitcnt lgkmcnt(0)
	v_mov_b32_e32 v0, 0x3500
	global_load_dword v0, v0, s[30:31] sc1
	s_add_u32 s12, s30, 0x3500
	s_addc_u32 s13, s31, 0
	s_waitcnt vmcnt(0)
	v_cmp_eq_u32_e32 vcc, v0, v1
	s_and_saveexec_b64 s[8:9], vcc
	s_cbranch_execz .LBB0_515
	s_mov_b32 s16, 1
	s_mov_b64 s[14:15], 0
	v_mov_b32_e32 v0, 0
	s_branch .LBB0_506

; __device__ __forceinline__ unsigned xb_ld(unsigned* p)              { return __hip_atomic_load(p, __ATOMIC_RELAXED, __HIP_MEMORY_SCOPE_AGENT); }
; __device__ __forceinline__ unsigned xb_add(unsigned* p, unsigned v) { return __hip_atomic_fetch_add(p, v, __ATOMIC_RELAXED, __HIP_MEMORY_SCOPE_AGENT); }
; #define XB_SPIN(cond, bar) do { unsigned _sp = 0; while (cond) { __builtin_amdgcn_s_sleep(1); \
;     if ((++_sp & 255u) == 0u) { if (xb_ld(&(bar)[XB_TMO])) break; if (_sp > XB_SPIN_CAP) { atomicAdd(&(bar)[XB_TMO], 1u); break; } } } } while (0)
; __device__ __forceinline__ void xcd_barrier(const XcdBarrier& b) {
;     ...
;         const unsigned old = xb_add(&bar[XB_XSUB(b.x)], 1u);
;         const unsigned gen = old / nloc;
;         if (old + 1u == (gen + 1u) * nloc) {
;             __builtin_amdgcn_fence(__ATOMIC_RELEASE, "agent");
;             asm volatile("s_waitcnt vmcnt(0)" ::: "memory");
;             const unsigned og = xb_add(&bar[XB_TOP], 1u);
;             const unsigned tg = og / nx;
;             if (og + 1u == (tg + 1u) * nx) xb_add(&bar[XB_TOPGEN], 1u);
;             else XB_SPIN(xb_ld(&bar[XB_TOPGEN]) == tg, bar);
;             __builtin_amdgcn_fence(__ATOMIC_ACQUIRE, "agent");
;             xb_add(&bar[XB_XGEN(b.x)], 1u);
;             asm volatile("s_waitcnt vmcnt(0)" ::: "memory");
;         } else {
;             XB_SPIN(xb_ld(&bar[XB_XGEN(b.x)]) == gen, bar);
.LBB0_763:
	s_or_b64 exec, exec, s[8:9]
	v_cvt_f32_u32_e32 v4, v2
	s_waitcnt vmcnt(0)
	v_readfirstlane_b32 s2, v3
	v_sub_u32_e32 v3, 0, v2
	v_rcp_iflag_f32_e32 v4, v4
	v_add_u32_e32 v5, s2, v1
	v_mul_f32_e32 v4, 0x4f7ffffe, v4
	v_cvt_u32_f32_e32 v4, v4
	v_mul_lo_u32 v1, v3, v4
	v_mul_hi_u32 v1, v4, v1
	v_add_u32_e32 v1, v4, v1
	v_mul_hi_u32 v1, v5, v1
	v_mul_lo_u32 v3, v1, v2
	v_sub_u32_e32 v3, v5, v3
	v_add_u32_e32 v4, 1, v1
	v_cmp_ge_u32_e32 vcc, v3, v2
	s_nop 1
	v_cndmask_b32_e32 v1, v1, v4, vcc
	v_sub_u32_e32 v4, v3, v2
	v_cndmask_b32_e32 v3, v3, v4, vcc
	v_add_u32_e32 v4, 1, v1
	v_cmp_ge_u32_e32 vcc, v3, v2
	v_add_u32_e32 v3, 1, v5
	s_nop 0
	v_cndmask_b32_e32 v1, v1, v4, vcc
	v_mul_lo_u32 v4, v2, v1
	v_add_u32_e32 v2, v4, v2
	v_cmp_ne_u32_e32 vcc, v3, v2
	s_and_saveexec_b64 s[6:7], vcc
	s_xor_b64 s[6:7], exec, s[6:7]
	s_cbranch_execz .LBB0_777
	s_waitcnt lgkmcnt(0)
	v_mov_b32_e32 v0, 0x3500
	global_load_dword v0, v0, s[30:31] sc1
	s_add_u32 s10, s30, 0x3500
	s_addc_u32 s11, s31, 0
	s_waitcnt vmcnt(0)
	v_cmp_eq_u32_e32 vcc, v0, v1
	s_and_saveexec_b64 s[8:9], vcc
	s_cbranch_execz .LBB0_776
	s_mov_b32 s2, 1
	s_mov_b64 s[12:13], 0
	v_mov_b32_e32 v0, 0
	s_branch .LBB0_767

; __device__ __forceinline__ unsigned xb_ld(unsigned* p)              { return __hip_atomic_load(p, __ATOMIC_RELAXED, __HIP_MEMORY_SCOPE_AGENT); }
; __device__ __forceinline__ unsigned xb_add(unsigned* p, unsigned v) { return __hip_atomic_fetch_add(p, v, __ATOMIC_RELAXED, __HIP_MEMORY_SCOPE_AGENT); }
; #define XB_SPIN(cond, bar) do { unsigned _sp = 0; while (cond) { __builtin_amdgcn_s_sleep(1); \
;     if ((++_sp & 255u) == 0u) { if (xb_ld(&(bar)[XB_TMO])) break; if (_sp > XB_SPIN_CAP) { atomicAdd(&(bar)[XB_TMO], 1u); break; } } } } while (0)
; __device__ __forceinline__ void xcd_barrier(const XcdBarrier& b) {
;     ...
;         const unsigned old = xb_add(&bar[XB_XSUB(b.x)], 1u);
;         const unsigned gen = old / nloc;
;         if (old + 1u == (gen + 1u) * nloc) {
;             __builtin_amdgcn_fence(__ATOMIC_RELEASE, "agent");
;             asm volatile("s_waitcnt vmcnt(0)" ::: "memory");
;             const unsigned og = xb_add(&bar[XB_TOP], 1u);
;             const unsigned tg = og / nx;
;             if (og + 1u == (tg + 1u) * nx) xb_add(&bar[XB_TOPGEN], 1u);
;             else XB_SPIN(xb_ld(&bar[XB_TOPGEN]) == tg, bar);
;             __builtin_amdgcn_fence(__ATOMIC_ACQUIRE, "agent");
;             xb_add(&bar[XB_XGEN(b.x)], 1u);
;             asm volatile("s_waitcnt vmcnt(0)" ::: "memory");
;         } else {
;             XB_SPIN(xb_ld(&bar[XB_XGEN(b.x)]) == gen, bar);
.LBB0_897:
	s_or_b64 exec, exec, s[10:11]
	v_cvt_f32_u32_e32 v4, v2
	s_waitcnt vmcnt(0)
	v_readfirstlane_b32 s2, v3
	v_sub_u32_e32 v3, 0, v2
	v_rcp_iflag_f32_e32 v4, v4
	v_add_u32_e32 v5, s2, v1
	v_mul_f32_e32 v4, 0x4f7ffffe, v4
	v_cvt_u32_f32_e32 v4, v4
	v_mul_lo_u32 v1, v3, v4
	v_mul_hi_u32 v1, v4, v1
	v_add_u32_e32 v1, v4, v1
	v_mul_hi_u32 v1, v5, v1
	v_mul_lo_u32 v3, v1, v2
	v_sub_u32_e32 v3, v5, v3
	v_add_u32_e32 v4, 1, v1
	v_cmp_ge_u32_e32 vcc, v3, v2
	s_nop 1
	v_cndmask_b32_e32 v1, v1, v4, vcc
	v_sub_u32_e32 v4, v3, v2
	v_cndmask_b32_e32 v3, v3, v4, vcc
	v_add_u32_e32 v4, 1, v1
	v_cmp_ge_u32_e32 vcc, v3, v2
	v_add_u32_e32 v3, 1, v5
	s_nop 0
	v_cndmask_b32_e32 v1, v1, v4, vcc
	v_mul_lo_u32 v4, v2, v1
	v_add_u32_e32 v2, v4, v2
	v_cmp_ne_u32_e32 vcc, v3, v2
	s_and_saveexec_b64 s[6:7], vcc
	s_xor_b64 s[6:7], exec, s[6:7]
	s_cbranch_execz .LBB0_911
	s_waitcnt lgkmcnt(0)
	v_mov_b32_e32 v0, 0x3500
	global_load_dword v0, v0, s[30:31] sc1
	s_add_u32 s12, s30, 0x3500
	s_addc_u32 s13, s31, 0
	s_waitcnt vmcnt(0)
	v_cmp_eq_u32_e32 vcc, v0, v1
	s_and_saveexec_b64 s[10:11], vcc
	s_cbranch_execz .LBB0_910
	s_mov_b32 s2, 1
	s_mov_b64 s[14:15], 0
	v_mov_b32_e32 v0, 0
	s_branch .LBB0_901

; __device__ __forceinline__ unsigned xb_ld(unsigned* p)              { return __hip_atomic_load(p, __ATOMIC_RELAXED, __HIP_MEMORY_SCOPE_AGENT); }
; __device__ __forceinline__ unsigned xb_add(unsigned* p, unsigned v) { return __hip_atomic_fetch_add(p, v, __ATOMIC_RELAXED, __HIP_MEMORY_SCOPE_AGENT); }
; #define XB_SPIN(cond, bar) do { unsigned _sp = 0; while (cond) { __builtin_amdgcn_s_sleep(1); \
;     if ((++_sp & 255u) == 0u) { if (xb_ld(&(bar)[XB_TMO])) break; if (_sp > XB_SPIN_CAP) { atomicAdd(&(bar)[XB_TMO], 1u); break; } } } } while (0)
; __device__ __forceinline__ void xcd_barrier(const XcdBarrier& b) {
;     ...
;         const unsigned old = xb_add(&bar[XB_XSUB(b.x)], 1u);
;         const unsigned gen = old / nloc;
;         if (old + 1u == (gen + 1u) * nloc) {
;             __builtin_amdgcn_fence(__ATOMIC_RELEASE, "agent");
;             asm volatile("s_waitcnt vmcnt(0)" ::: "memory");
;             const unsigned og = xb_add(&bar[XB_TOP], 1u);
;             const unsigned tg = og / nx;
;             if (og + 1u == (tg + 1u) * nx) xb_add(&bar[XB_TOPGEN], 1u);
;             else XB_SPIN(xb_ld(&bar[XB_TOPGEN]) == tg, bar);
;             __builtin_amdgcn_fence(__ATOMIC_ACQUIRE, "agent");
;             xb_add(&bar[XB_XGEN(b.x)], 1u);
;             asm volatile("s_waitcnt vmcnt(0)" ::: "memory");
;         } else {
;             XB_SPIN(xb_ld(&bar[XB_XGEN(b.x)]) == gen, bar);
.LBB0_1062:
	s_or_b64 exec, exec, s[10:11]
	v_cvt_f32_u32_e32 v4, v2
	s_waitcnt vmcnt(0)
	v_readfirstlane_b32 s2, v3
	v_sub_u32_e32 v3, 0, v2
	v_rcp_iflag_f32_e32 v4, v4
	v_add_u32_e32 v5, s2, v1
	v_mul_f32_e32 v4, 0x4f7ffffe, v4
	v_cvt_u32_f32_e32 v4, v4
	v_mul_lo_u32 v1, v3, v4
	v_mul_hi_u32 v1, v4, v1
	v_add_u32_e32 v1, v4, v1
	v_mul_hi_u32 v1, v5, v1
	v_mul_lo_u32 v3, v1, v2
	v_sub_u32_e32 v3, v5, v3
	v_add_u32_e32 v4, 1, v1
	v_cmp_ge_u32_e32 vcc, v3, v2
	s_nop 1
	v_cndmask_b32_e32 v1, v1, v4, vcc
	v_sub_u32_e32 v4, v3, v2
	v_cndmask_b32_e32 v3, v3, v4, vcc
	v_add_u32_e32 v4, 1, v1
	v_cmp_ge_u32_e32 vcc, v3, v2
	v_add_u32_e32 v3, 1, v5
	s_nop 0
	v_cndmask_b32_e32 v1, v1, v4, vcc
	v_mul_lo_u32 v4, v2, v1
	v_add_u32_e32 v2, v4, v2
	v_cmp_ne_u32_e32 vcc, v3, v2
	s_and_saveexec_b64 s[8:9], vcc
	s_xor_b64 s[8:9], exec, s[8:9]
	s_cbranch_execz .LBB0_1076
	s_waitcnt lgkmcnt(0)
	v_mov_b32_e32 v0, 0x3500
	global_load_dword v0, v0, s[30:31] sc1
	s_add_u32 s12, s30, 0x3500
	s_addc_u32 s13, s31, 0
	s_waitcnt vmcnt(0)
	v_cmp_eq_u32_e32 vcc, v0, v1
	s_and_saveexec_b64 s[10:11], vcc
	s_cbranch_execz .LBB0_1075
	s_mov_b32 s2, 1
	s_mov_b64 s[14:15], 0
	v_mov_b32_e32 v0, 0
	s_branch .LBB0_1066

; __device__ __forceinline__ unsigned xb_ld(unsigned* p)              { return __hip_atomic_load(p, __ATOMIC_RELAXED, __HIP_MEMORY_SCOPE_AGENT); }
; __device__ __forceinline__ unsigned xb_add(unsigned* p, unsigned v) { return __hip_atomic_fetch_add(p, v, __ATOMIC_RELAXED, __HIP_MEMORY_SCOPE_AGENT); }
; #define XB_SPIN(cond, bar) do { unsigned _sp = 0; while (cond) { __builtin_amdgcn_s_sleep(1); \
;     if ((++_sp & 255u) == 0u) { if (xb_ld(&(bar)[XB_TMO])) break; if (_sp > XB_SPIN_CAP) { atomicAdd(&(bar)[XB_TMO], 1u); break; } } } } while (0)
; __device__ __forceinline__ void xcd_barrier(const XcdBarrier& b) {
;     ...
;         const unsigned old = xb_add(&bar[XB_XSUB(b.x)], 1u);
;         const unsigned gen = old / nloc;
;         if (old + 1u == (gen + 1u) * nloc) {
;             __builtin_amdgcn_fence(__ATOMIC_RELEASE, "agent");
;             asm volatile("s_waitcnt vmcnt(0)" ::: "memory");
;             const unsigned og = xb_add(&bar[XB_TOP], 1u);
;             const unsigned tg = og / nx;
;             if (og + 1u == (tg + 1u) * nx) xb_add(&bar[XB_TOPGEN], 1u);
;             else XB_SPIN(xb_ld(&bar[XB_TOPGEN]) == tg, bar);
;             __builtin_amdgcn_fence(__ATOMIC_ACQUIRE, "agent");
;             xb_add(&bar[XB_XGEN(b.x)], 1u);
;             asm volatile("s_waitcnt vmcnt(0)" ::: "memory");
;         } else {
;             XB_SPIN(xb_ld(&bar[XB_XGEN(b.x)]) == gen, bar);
.LBB0_1193:
	s_or_b64 exec, exec, s[12:13]
	v_cvt_f32_u32_e32 v4, v2
	s_waitcnt vmcnt(0)
	v_readfirstlane_b32 s2, v3
	v_sub_u32_e32 v3, 0, v2
	v_rcp_iflag_f32_e32 v4, v4
	v_add_u32_e32 v5, s2, v1
	v_mul_f32_e32 v4, 0x4f7ffffe, v4
	v_cvt_u32_f32_e32 v4, v4
	v_mul_lo_u32 v1, v3, v4
	v_mul_hi_u32 v1, v4, v1
	v_add_u32_e32 v1, v4, v1
	v_mul_hi_u32 v1, v5, v1
	v_mul_lo_u32 v3, v1, v2
	v_sub_u32_e32 v3, v5, v3
	v_add_u32_e32 v4, 1, v1
	v_cmp_ge_u32_e32 vcc, v3, v2
	s_nop 1
	v_cndmask_b32_e32 v1, v1, v4, vcc
	v_sub_u32_e32 v4, v3, v2
	v_cndmask_b32_e32 v3, v3, v4, vcc
	v_add_u32_e32 v4, 1, v1
	v_cmp_ge_u32_e32 vcc, v3, v2
	v_add_u32_e32 v3, 1, v5
	s_nop 0
	v_cndmask_b32_e32 v1, v1, v4, vcc
	v_mul_lo_u32 v4, v2, v1
	v_add_u32_e32 v2, v4, v2
	v_cmp_ne_u32_e32 vcc, v3, v2
	s_and_saveexec_b64 s[10:11], vcc
	s_xor_b64 s[10:11], exec, s[10:11]
	s_cbranch_execz .LBB0_1207
	s_waitcnt lgkmcnt(0)
	v_mov_b32_e32 v0, 0x3500
	global_load_dword v0, v0, s[30:31] sc1
	s_add_u32 s14, s30, 0x3500
	s_addc_u32 s15, s31, 0
	s_waitcnt vmcnt(0)
	v_cmp_eq_u32_e32 vcc, v0, v1
	s_and_saveexec_b64 s[12:13], vcc
	s_cbranch_execz .LBB0_1206
	s_mov_b32 s2, 1
	s_mov_b64 s[36:37], 0
	v_mov_b32_e32 v0, 0
	s_branch .LBB0_1197

; __device__ __forceinline__ unsigned xb_ld(unsigned* p)              { return __hip_atomic_load(p, __ATOMIC_RELAXED, __HIP_MEMORY_SCOPE_AGENT); }
; __device__ __forceinline__ unsigned xb_add(unsigned* p, unsigned v) { return __hip_atomic_fetch_add(p, v, __ATOMIC_RELAXED, __HIP_MEMORY_SCOPE_AGENT); }
; #define XB_SPIN(cond, bar) do { unsigned _sp = 0; while (cond) { __builtin_amdgcn_s_sleep(1); \
;     if ((++_sp & 255u) == 0u) { if (xb_ld(&(bar)[XB_TMO])) break; if (_sp > XB_SPIN_CAP) { atomicAdd(&(bar)[XB_TMO], 1u); break; } } } } while (0)
; __device__ __forceinline__ void xcd_barrier(const XcdBarrier& b) {
;     ...
;         const unsigned old = xb_add(&bar[XB_XSUB(b.x)], 1u);
;         const unsigned gen = old / nloc;
;         if (old + 1u == (gen + 1u) * nloc) {
;             __builtin_amdgcn_fence(__ATOMIC_RELEASE, "agent");
;             asm volatile("s_waitcnt vmcnt(0)" ::: "memory");
;             const unsigned og = xb_add(&bar[XB_TOP], 1u);
;             const unsigned tg = og / nx;
;             if (og + 1u == (tg + 1u) * nx) xb_add(&bar[XB_TOPGEN], 1u);
;             else XB_SPIN(xb_ld(&bar[XB_TOPGEN]) == tg, bar);
;             __builtin_amdgcn_fence(__ATOMIC_ACQUIRE, "agent");
;             xb_add(&bar[XB_XGEN(b.x)], 1u);
;             asm volatile("s_waitcnt vmcnt(0)" ::: "memory");
;         } else {
;             XB_SPIN(xb_ld(&bar[XB_XGEN(b.x)]) == gen, bar);
.LBB0_1261:
	s_or_b64 exec, exec, s[12:13]
	v_cvt_f32_u32_e32 v4, v2
	s_waitcnt vmcnt(0)
	v_readfirstlane_b32 s2, v3
	v_sub_u32_e32 v3, 0, v2
	v_rcp_iflag_f32_e32 v4, v4
	v_add_u32_e32 v5, s2, v1
	v_mul_f32_e32 v4, 0x4f7ffffe, v4
	v_cvt_u32_f32_e32 v4, v4
	v_mul_lo_u32 v1, v3, v4
	v_mul_hi_u32 v1, v4, v1
	v_add_u32_e32 v1, v4, v1
	v_mul_hi_u32 v1, v5, v1
	v_mul_lo_u32 v3, v1, v2
	v_sub_u32_e32 v3, v5, v3
	v_add_u32_e32 v4, 1, v1
	v_cmp_ge_u32_e32 vcc, v3, v2
	s_nop 1
	v_cndmask_b32_e32 v1, v1, v4, vcc
	v_sub_u32_e32 v4, v3, v2
	v_cndmask_b32_e32 v3, v3, v4, vcc
	v_add_u32_e32 v4, 1, v1
	v_cmp_ge_u32_e32 vcc, v3, v2
	v_add_u32_e32 v3, 1, v5
	s_nop 0
	v_cndmask_b32_e32 v1, v1, v4, vcc
	v_mul_lo_u32 v4, v2, v1
	v_add_u32_e32 v2, v4, v2
	v_cmp_ne_u32_e32 vcc, v3, v2
	s_and_saveexec_b64 s[2:3], vcc
	s_xor_b64 s[10:11], exec, s[2:3]
	s_cbranch_execz .LBB0_1275
	s_waitcnt lgkmcnt(0)
	v_mov_b32_e32 v0, 0x3500
	global_load_dword v0, v0, s[30:31] sc1
	s_add_u32 s14, s30, 0x3500
	s_addc_u32 s15, s31, 0
	s_waitcnt vmcnt(0)
	v_cmp_eq_u32_e32 vcc, v0, v1
	s_and_saveexec_b64 s[12:13], vcc
	s_cbranch_execz .LBB0_1274
	s_mov_b32 s2, 1
	s_mov_b64 s[36:37], 0
	v_mov_b32_e32 v0, 0
	s_branch .LBB0_1265

; __device__ __forceinline__ unsigned xb_ld(unsigned* p)              { return __hip_atomic_load(p, __ATOMIC_RELAXED, __HIP_MEMORY_SCOPE_AGENT); }
; __device__ __forceinline__ unsigned xb_add(unsigned* p, unsigned v) { return __hip_atomic_fetch_add(p, v, __ATOMIC_RELAXED, __HIP_MEMORY_SCOPE_AGENT); }
; #define XB_SPIN(cond, bar) do { unsigned _sp = 0; while (cond) { __builtin_amdgcn_s_sleep(1); \
;     if ((++_sp & 255u) == 0u) { if (xb_ld(&(bar)[XB_TMO])) break; if (_sp > XB_SPIN_CAP) { atomicAdd(&(bar)[XB_TMO], 1u); break; } } } } while (0)
; __device__ __forceinline__ void xcd_barrier(const XcdBarrier& b) {
;     ...
;         const unsigned old = xb_add(&bar[XB_XSUB(b.x)], 1u);
;         const unsigned gen = old / nloc;
;         if (old + 1u == (gen + 1u) * nloc) {
;             __builtin_amdgcn_fence(__ATOMIC_RELEASE, "agent");
;             asm volatile("s_waitcnt vmcnt(0)" ::: "memory");
;             const unsigned og = xb_add(&bar[XB_TOP], 1u);
;             const unsigned tg = og / nx;
;             if (og + 1u == (tg + 1u) * nx) xb_add(&bar[XB_TOPGEN], 1u);
;             else XB_SPIN(xb_ld(&bar[XB_TOPGEN]) == tg, bar);
;             __builtin_amdgcn_fence(__ATOMIC_ACQUIRE, "agent");
;             xb_add(&bar[XB_XGEN(b.x)], 1u);
;             asm volatile("s_waitcnt vmcnt(0)" ::: "memory");
;         } else {
;             XB_SPIN(xb_ld(&bar[XB_XGEN(b.x)]) == gen, bar);
.LBB0_1341:
	s_or_b64 exec, exec, s[8:9]
	v_cvt_f32_u32_e32 v4, v2
	s_waitcnt vmcnt(0)
	v_readfirstlane_b32 s6, v3
	v_sub_u32_e32 v3, 0, v2
	v_rcp_iflag_f32_e32 v4, v4
	v_add_u32_e32 v5, s6, v1
	v_mul_f32_e32 v4, 0x4f7ffffe, v4
	v_cvt_u32_f32_e32 v4, v4
	v_mul_lo_u32 v1, v3, v4
	v_mul_hi_u32 v1, v4, v1
	v_add_u32_e32 v1, v4, v1
	v_mul_hi_u32 v1, v5, v1
	v_mul_lo_u32 v3, v1, v2
	v_sub_u32_e32 v3, v5, v3
	v_add_u32_e32 v4, 1, v1
	v_cmp_ge_u32_e32 vcc, v3, v2
	s_nop 1
	v_cndmask_b32_e32 v1, v1, v4, vcc
	v_sub_u32_e32 v4, v3, v2
	v_cndmask_b32_e32 v3, v3, v4, vcc
	v_add_u32_e32 v4, 1, v1
	v_cmp_ge_u32_e32 vcc, v3, v2
	v_add_u32_e32 v3, 1, v5
	s_nop 0
	v_cndmask_b32_e32 v1, v1, v4, vcc
	v_mul_lo_u32 v4, v2, v1
	v_add_u32_e32 v2, v4, v2
	v_cmp_ne_u32_e32 vcc, v3, v2
	s_and_saveexec_b64 s[6:7], vcc
	s_xor_b64 s[6:7], exec, s[6:7]
	s_cbranch_execz .LBB0_1355
	s_waitcnt lgkmcnt(0)
	v_mov_b32_e32 v0, 0x3500
	global_load_dword v0, v0, s[30:31] sc1
	s_add_u32 s10, s30, 0x3500
	s_addc_u32 s11, s31, 0
	s_waitcnt vmcnt(0)
	v_cmp_eq_u32_e32 vcc, v0, v1
	s_and_saveexec_b64 s[8:9], vcc
	s_cbranch_execz .LBB0_1354
	s_mov_b32 s20, 1
	s_mov_b64 s[12:13], 0
	v_mov_b32_e32 v0, 0
	s_branch .LBB0_1345
